# combo: stag2+prio K-loops with peeled zero-init-free first iteration, batched up-proj gate loads, batched FFN-out residual loads
# speedup vs baseline: 1.0138x; 1.0091x over previous
.LBB0_273:
	v_add_u32_e32 v144, v151, v182
	v_or_b32_e32 v146, 0x18000, v144
	v_add_u32_e32 v144, 0x18800, v144
	ds_read_b128 v[146:149], v146
	ds_read_b128 v[176:179], v144
	v_add3_u32 v144, v99, v182, s81
	ds_read_b128 v[180:183], v144
	ds_read_b128 v[184:187], v144 offset:2048
	ds_read_b128 v[206:209], v144 offset:4096
	ds_read_b128 v[216:219], v144 offset:6144
	s_waitcnt lgkmcnt(0)
	v_mfma_f32_16x16x32_bf16 v[60:63], v[146:149], v[180:183], v[60:63]
	v_mfma_f32_16x16x32_bf16 v[56:59], v[176:179], v[180:183], v[56:59]
	v_mfma_f32_16x16x32_bf16 v[52:55], v[146:149], v[184:187], v[52:55]
	v_mfma_f32_16x16x32_bf16 v[48:51], v[176:179], v[184:187], v[48:51]
	v_mfma_f32_16x16x32_bf16 v[44:47], v[146:149], v[206:209], v[44:47]
	v_mfma_f32_16x16x32_bf16 v[40:43], v[176:179], v[206:209], v[40:43]
	v_mfma_f32_16x16x32_bf16 v[36:39], v[146:149], v[216:219], v[36:39]
	v_mfma_f32_16x16x32_bf16 v[32:35], v[176:179], v[216:219], v[32:35]
	ds_read_b128 v[180:183], v144 offset:8192
	ds_read_b128 v[184:187], v144 offset:10240
	ds_read_b128 v[206:209], v144 offset:12288
	ds_read_b128 v[216:219], v144 offset:14336
	s_waitcnt lgkmcnt(0)
	v_mfma_f32_16x16x32_bf16 v[28:31], v[146:149], v[180:183], v[28:31]
	v_mfma_f32_16x16x32_bf16 v[24:27], v[176:179], v[180:183], v[24:27]
	v_mfma_f32_16x16x32_bf16 v[20:23], v[146:149], v[184:187], v[20:23]
	v_mfma_f32_16x16x32_bf16 v[16:19], v[176:179], v[184:187], v[16:19]
	v_mfma_f32_16x16x32_bf16 v[12:15], v[146:149], v[206:209], v[12:15]
	v_mfma_f32_16x16x32_bf16 v[8:11], v[176:179], v[206:209], v[8:11]
	v_mfma_f32_16x16x32_bf16 v[4:7], v[146:149], v[216:219], v[4:7]
	v_mfma_f32_16x16x32_bf16 v[0:3], v[176:179], v[216:219], v[0:3]
	v_add_u32_e32 v144, v151, v107
	v_or_b32_e32 v146, 0x18000, v144
	v_add3_u32 v99, v99, v107, s81
	v_add_u32_e32 v144, 0x18800, v144
	ds_read_b128 v[146:149], v146
	ds_read_b128 v[176:179], v144
	ds_read_b128 v[180:183], v99
	ds_read_b128 v[184:187], v99 offset:2048
	ds_read_b128 v[206:209], v99 offset:4096
	ds_read_b128 v[216:219], v99 offset:6144
	s_waitcnt lgkmcnt(0)
	v_mfma_f32_16x16x32_bf16 v[60:63], v[146:149], v[180:183], v[60:63]
	v_mfma_f32_16x16x32_bf16 v[56:59], v[176:179], v[180:183], v[56:59]
	v_mfma_f32_16x16x32_bf16 v[52:55], v[146:149], v[184:187], v[52:55]
	v_mfma_f32_16x16x32_bf16 v[48:51], v[176:179], v[184:187], v[48:51]
	v_mfma_f32_16x16x32_bf16 v[44:47], v[146:149], v[206:209], v[44:47]
	v_mfma_f32_16x16x32_bf16 v[40:43], v[176:179], v[206:209], v[40:43]
	v_mfma_f32_16x16x32_bf16 v[180:183], v[146:149], v[216:219], v[36:39]
	v_mfma_f32_16x16x32_bf16 v[32:35], v[176:179], v[216:219], v[32:35]
	s_nop 1
	ds_read_b128 v[36:39], v99 offset:8192
	ds_read_b128 v[184:187], v99 offset:10240
	ds_read_b128 v[206:209], v99 offset:12288
	ds_read_b128 v[216:219], v99 offset:14336
	s_waitcnt lgkmcnt(0)
	v_mfma_f32_16x16x32_bf16 v[28:31], v[146:149], v[36:39], v[28:31]
	v_mfma_f32_16x16x32_bf16 v[24:27], v[176:179], v[36:39], v[24:27]
	v_mfma_f32_16x16x32_bf16 v[20:23], v[146:149], v[184:187], v[20:23]
	v_mfma_f32_16x16x32_bf16 v[16:19], v[176:179], v[184:187], v[16:19]
	v_mfma_f32_16x16x32_bf16 v[12:15], v[146:149], v[206:209], v[12:15]
	v_mfma_f32_16x16x32_bf16 v[8:11], v[176:179], v[206:209], v[8:11]
	v_mfma_f32_16x16x32_bf16 v[4:7], v[146:149], v[216:219], v[4:7]
	v_mfma_f32_16x16x32_bf16 v[0:3], v[176:179], v[216:219], v[0:3]
	s_lshl_b32 s0, s69, 11
	v_lshl_add_u64 v[36:37], v[112:113], 0, s[0:1]
	v_lshl_add_u64 v[38:39], v[36:37], 0, v[118:119]
	global_load_dwordx2 v[216:217], v[38:39], off
	global_load_dwordx2 v[218:219], v[38:39], off offset:32
	v_lshl_add_u64 v[38:39], v[36:37], 0, v[120:121]
	global_load_dwordx2 v[220:221], v[38:39], off
	global_load_dwordx2 v[222:223], v[38:39], off offset:32
	v_lshl_add_u64 v[38:39], v[36:37], 0, v[126:127]
	global_load_dwordx2 v[224:225], v[38:39], off
	global_load_dwordx2 v[226:227], v[38:39], off offset:32
	v_lshl_add_u64 v[38:39], v[36:37], 0, v[128:129]
	global_load_dwordx2 v[228:229], v[38:39], off
	global_load_dwordx2 v[230:231], v[38:39], off offset:32
	v_lshl_add_u64 v[38:39], v[36:37], 0, v[134:135]
	global_load_dwordx2 v[232:233], v[38:39], off
	global_load_dwordx2 v[234:235], v[38:39], off offset:32
	v_lshl_add_u64 v[38:39], v[36:37], 0, v[136:137]
	global_load_dwordx2 v[236:237], v[38:39], off
	global_load_dwordx2 v[238:239], v[38:39], off offset:32
	v_lshl_add_u64 v[38:39], v[36:37], 0, v[142:143]
	global_load_dwordx2 v[240:241], v[38:39], off
	global_load_dwordx2 v[242:243], v[38:39], off offset:32
	v_lshl_add_u64 v[38:39], v[36:37], 0, v[154:155]
	global_load_dwordx2 v[244:245], v[38:39], off
	global_load_dwordx2 v[246:247], v[38:39], off offset:32
	s_add_i32 s69, s69, 1
	s_add_u32 s24, s24, 0x100000
	s_addc_u32 s25, s25, 0
	s_cmp_eq_u32 s69, 3
	s_waitcnt vmcnt(0)
	v_lshlrev_b32_e32 v146, 16, v216
	v_and_b32_e32 v147, 0xffff0000, v216
	v_pk_fma_f32 v[174:175], v[60:61], v[146:147], v[174:175]
	v_lshlrev_b32_e32 v148, 16, v219
	v_and_b32_e32 v149, 0xffff0000, v219
	v_pk_fma_f32 v[168:169], v[58:59], v[148:149], v[168:169]
	v_lshlrev_b32_e32 v146, 16, v218
	v_and_b32_e32 v147, 0xffff0000, v218
	v_pk_fma_f32 v[170:171], v[56:57], v[146:147], v[170:171]
	v_lshlrev_b32_e32 v148, 16, v217
	v_and_b32_e32 v149, 0xffff0000, v217
	v_pk_fma_f32 v[172:173], v[62:63], v[148:149], v[172:173]
	v_lshlrev_b32_e32 v146, 16, v220
	v_and_b32_e32 v147, 0xffff0000, v220
	v_pk_fma_f32 v[166:167], v[52:53], v[146:147], v[166:167]
	v_lshlrev_b32_e32 v148, 16, v223
	v_and_b32_e32 v149, 0xffff0000, v223
	v_pk_fma_f32 v[160:161], v[50:51], v[148:149], v[160:161]
	v_lshlrev_b32_e32 v146, 16, v222
	v_and_b32_e32 v147, 0xffff0000, v222
	v_pk_fma_f32 v[162:163], v[48:49], v[146:147], v[162:163]
	v_lshlrev_b32_e32 v148, 16, v221
	v_and_b32_e32 v149, 0xffff0000, v221
	v_pk_fma_f32 v[164:165], v[54:55], v[148:149], v[164:165]
	v_lshlrev_b32_e32 v146, 16, v224
	v_and_b32_e32 v147, 0xffff0000, v224
	v_pk_fma_f32 v[158:159], v[44:45], v[146:147], v[158:159]
	v_lshlrev_b32_e32 v148, 16, v227
	v_and_b32_e32 v149, 0xffff0000, v227
	v_pk_fma_f32 v[138:139], v[42:43], v[148:149], v[138:139]
	v_lshlrev_b32_e32 v146, 16, v226
	v_and_b32_e32 v147, 0xffff0000, v226
	v_pk_fma_f32 v[140:141], v[40:41], v[146:147], v[140:141]
	v_lshlrev_b32_e32 v148, 16, v225
	v_and_b32_e32 v149, 0xffff0000, v225
	v_pk_fma_f32 v[156:157], v[46:47], v[148:149], v[156:157]
	v_lshlrev_b32_e32 v146, 16, v229
	v_and_b32_e32 v147, 0xffff0000, v229
	v_pk_fma_f32 v[130:131], v[182:183], v[146:147], v[130:131]
	v_lshlrev_b32_e32 v148, 16, v230
	v_and_b32_e32 v149, 0xffff0000, v230
	v_pk_fma_f32 v[124:125], v[32:33], v[148:149], v[124:125]
	v_lshlrev_b32_e32 v146, 16, v231
	v_and_b32_e32 v147, 0xffff0000, v231
	v_pk_fma_f32 v[122:123], v[34:35], v[146:147], v[122:123]
	v_lshlrev_b32_e32 v148, 16, v228
	v_and_b32_e32 v149, 0xffff0000, v228
	v_pk_fma_f32 v[132:133], v[180:181], v[148:149], v[132:133]
	v_lshlrev_b32_e32 v146, 16, v232
	v_and_b32_e32 v147, 0xffff0000, v232
	v_pk_fma_f32 v[116:117], v[28:29], v[146:147], v[116:117]
	v_lshlrev_b32_e32 v148, 16, v233
	v_and_b32_e32 v149, 0xffff0000, v233
	v_pk_fma_f32 v[114:115], v[30:31], v[148:149], v[114:115]
	v_lshlrev_b32_e32 v146, 16, v234
	v_and_b32_e32 v147, 0xffff0000, v234
	v_pk_fma_f32 v[110:111], v[24:25], v[146:147], v[110:111]
	v_lshlrev_b32_e32 v148, 16, v235
	v_and_b32_e32 v149, 0xffff0000, v235
	v_pk_fma_f32 v[108:109], v[26:27], v[148:149], v[108:109]
	v_lshlrev_b32_e32 v146, 16, v236
	v_and_b32_e32 v147, 0xffff0000, v236
	v_pk_fma_f32 v[104:105], v[20:21], v[146:147], v[104:105]
	v_lshlrev_b32_e32 v148, 16, v237
	v_and_b32_e32 v149, 0xffff0000, v237
	v_pk_fma_f32 v[102:103], v[22:23], v[148:149], v[102:103]
	v_lshlrev_b32_e32 v146, 16, v238
	v_and_b32_e32 v147, 0xffff0000, v238
	v_pk_fma_f32 v[94:95], v[16:17], v[146:147], v[94:95]
	v_lshlrev_b32_e32 v148, 16, v239
	v_and_b32_e32 v149, 0xffff0000, v239
	v_pk_fma_f32 v[92:93], v[18:19], v[148:149], v[92:93]
	v_lshlrev_b32_e32 v146, 16, v240
	v_and_b32_e32 v147, 0xffff0000, v240
	v_pk_fma_f32 v[86:87], v[12:13], v[146:147], v[86:87]
	v_lshlrev_b32_e32 v148, 16, v241
	v_and_b32_e32 v149, 0xffff0000, v241
	v_pk_fma_f32 v[84:85], v[14:15], v[148:149], v[84:85]
	v_lshlrev_b32_e32 v146, 16, v242
	v_and_b32_e32 v147, 0xffff0000, v242
	v_pk_fma_f32 v[80:81], v[8:9], v[146:147], v[80:81]
	v_lshlrev_b32_e32 v148, 16, v243
	v_and_b32_e32 v149, 0xffff0000, v243
	v_pk_fma_f32 v[78:79], v[10:11], v[148:149], v[78:79]
	v_lshlrev_b32_e32 v146, 16, v244
	v_and_b32_e32 v147, 0xffff0000, v244
	v_pk_fma_f32 v[74:75], v[4:5], v[146:147], v[74:75]
	v_lshlrev_b32_e32 v148, 16, v245
	v_and_b32_e32 v149, 0xffff0000, v245
	v_pk_fma_f32 v[72:73], v[6:7], v[148:149], v[72:73]
	v_lshlrev_b32_e32 v146, 16, v247
	v_and_b32_e32 v147, 0xffff0000, v247
	v_pk_fma_f32 v[68:69], v[2:3], v[146:147], v[68:69]
	v_lshlrev_b32_e32 v148, 16, v246
	v_and_b32_e32 v149, 0xffff0000, v246
	v_pk_fma_f32 v[66:67], v[0:1], v[148:149], v[66:67]
	s_cbranch_scc1 .LBB0_271

.LBB0_503:
	s_nop 1
	v_mov_b32_e32 v128, v190
	s_lshl_b32 s2, s2, 8
	s_lshl_b32 s3, s35, 8
	v_ashrrev_i32_e32 v129, 1, v128
	v_bfe_u32 v138, v128, 6, 2
	v_bfe_u32 v139, v128, 4, 2
	v_and_b32_e32 v129, 0xffffff80, v129
	v_and_or_b32 v128, v128, 15, s2
	v_add_u32_e32 v130, v128, v129
	s_ashr_i32 s2, s3, 31
	v_lshlrev_b32_e32 v128, 6, v138
	v_lshlrev_b32_e32 v129, 2, v139
	v_ashrrev_i32_e32 v131, 31, v130
	v_or3_b32 v128, s3, v128, v129
	v_mov_b32_e32 v129, s2
	v_lshlrev_b64 v[132:133], 10, v[130:131]
	v_lshl_add_u64 v[136:137], v[128:129], 0, v[132:133]
	v_lshlrev_b64 v[134:135], 2, v[136:137]
	v_lshl_add_u64 v[132:133], s[26:27], 0, v[134:135]
	global_load_dwordx4 v[228:231], v[132:133], off
	global_load_dwordx4 v[232:235], v[132:133], off offset:64
	global_load_dwordx4 v[236:239], v[132:133], off offset:128
	global_load_dwordx4 v[240:243], v[132:133], off offset:192
	v_cndmask_b32_e64 v144, 0, 1, s[24:25]
	v_cmp_ne_u32_e64 s[6:7], 1, v144
	s_andn2_b64 vcc, exec, s[24:25]
	v_lshl_add_u64 v[134:135], s[90:91], 0, v[134:135]
	s_mov_b64 s[2:3], -1
	s_waitcnt vmcnt(3)
	v_pk_fma_f32 v[122:123], v[122:123], 0.5, v[230:231] op_sel_hi:[1,0,1]
	v_pk_fma_f32 v[120:121], v[120:121], 0.5, v[228:229] op_sel_hi:[1,0,1]
	global_store_dwordx4 v[134:135], v[120:123], off
	s_cbranch_vccnz .LBB0_505
	s_mov_b64 s[2:3], 0

.LBB0_507:
	s_and_b64 vcc, exec, s[6:7]
	s_mov_b64 s[2:3], -1
	s_waitcnt vmcnt(3)
	v_pk_fma_f32 v[126:127], v[126:127], 0.5, v[234:235] op_sel_hi:[1,0,1]
	v_pk_fma_f32 v[124:125], v[124:125], 0.5, v[232:233] op_sel_hi:[1,0,1]
	global_store_dwordx4 v[134:135], v[124:127], off offset:64
	s_cbranch_vccnz .LBB0_509
	s_mov_b64 s[2:3], 0

.LBB0_511:
	s_and_b64 vcc, exec, s[6:7]
	s_mov_b64 s[2:3], -1
	s_waitcnt vmcnt(3)
	v_pk_fma_f32 v[118:119], v[118:119], 0.5, v[238:239] op_sel_hi:[1,0,1]
	v_pk_fma_f32 v[116:117], v[116:117], 0.5, v[236:237] op_sel_hi:[1,0,1]
	global_store_dwordx4 v[134:135], v[116:119], off offset:128
	s_cbranch_vccnz .LBB0_513
	s_mov_b64 s[2:3], 0

.LBB0_515:
	s_and_b64 vcc, exec, s[6:7]
	s_mov_b64 s[2:3], -1
	s_waitcnt vmcnt(3)
	v_pk_fma_f32 v[114:115], v[114:115], 0.5, v[242:243] op_sel_hi:[1,0,1]
	v_pk_fma_f32 v[112:113], v[112:113], 0.5, v[240:241] op_sel_hi:[1,0,1]
	global_store_dwordx4 v[134:135], v[112:115], off offset:192
	s_cbranch_vccnz .LBB0_517
	s_mov_b64 s[2:3], 0

.LBB0_521:
	s_or_b64 exec, exec, s[2:3]
	v_or_b32_e32 v114, 16, v130
	s_waitcnt lgkmcnt(0)
	v_ashrrev_i32_e32 v115, 31, v114
	v_lshlrev_b64 v[114:115], 10, v[114:115]
	v_lshl_add_u64 v[118:119], v[128:129], 0, v[114:115]
	v_lshlrev_b64 v[116:117], 2, v[118:119]
	v_lshl_add_u64 v[114:115], s[26:27], 0, v[116:117]
	global_load_dwordx4 v[228:231], v[114:115], off
	global_load_dwordx4 v[232:235], v[114:115], off offset:64
	global_load_dwordx4 v[236:239], v[114:115], off offset:128
	global_load_dwordx4 v[240:243], v[114:115], off offset:192
	s_and_b64 vcc, exec, s[6:7]
	v_lshl_add_u64 v[116:117], s[90:91], 0, v[116:117]
	s_mov_b64 s[2:3], -1
	s_waitcnt vmcnt(3)
	v_pk_fma_f32 v[110:111], v[110:111], 0.5, v[230:231] op_sel_hi:[1,0,1]
	v_pk_fma_f32 v[108:109], v[108:109], 0.5, v[228:229] op_sel_hi:[1,0,1]
	global_store_dwordx4 v[116:117], v[108:111], off
	s_cbranch_vccnz .LBB0_523
	s_mov_b64 s[2:3], 0

.LBB0_525:
	s_and_b64 vcc, exec, s[6:7]
	s_mov_b64 s[2:3], -1
	s_waitcnt vmcnt(3)
	v_pk_fma_f32 v[106:107], v[106:107], 0.5, v[234:235] op_sel_hi:[1,0,1]
	v_pk_fma_f32 v[104:105], v[104:105], 0.5, v[232:233] op_sel_hi:[1,0,1]
	global_store_dwordx4 v[116:117], v[104:107], off offset:64
	s_cbranch_vccnz .LBB0_527
	s_mov_b64 s[2:3], 0

.LBB0_529:
	s_and_b64 vcc, exec, s[6:7]
	s_mov_b64 s[2:3], -1
	s_waitcnt vmcnt(3)
	v_pk_fma_f32 v[102:103], v[102:103], 0.5, v[238:239] op_sel_hi:[1,0,1]
	v_pk_fma_f32 v[100:101], v[100:101], 0.5, v[236:237] op_sel_hi:[1,0,1]
	global_store_dwordx4 v[116:117], v[100:103], off offset:128
	s_cbranch_vccnz .LBB0_531
	s_mov_b64 s[2:3], 0

.LBB0_533:
	s_and_b64 vcc, exec, s[6:7]
	s_mov_b64 s[2:3], -1
	s_waitcnt vmcnt(3)
	v_pk_fma_f32 v[98:99], v[98:99], 0.5, v[242:243] op_sel_hi:[1,0,1]
	v_pk_fma_f32 v[96:97], v[96:97], 0.5, v[240:241] op_sel_hi:[1,0,1]
	global_store_dwordx4 v[116:117], v[96:99], off offset:192
	s_cbranch_vccnz .LBB0_535
	s_mov_b64 s[2:3], 0

.LBB0_539:
	s_or_b64 exec, exec, s[2:3]
	v_or_b32_e32 v96, 32, v130
	s_waitcnt lgkmcnt(0)
	v_ashrrev_i32_e32 v97, 31, v96
	v_lshlrev_b64 v[96:97], 10, v[96:97]
	v_lshl_add_u64 v[100:101], v[128:129], 0, v[96:97]
	v_lshlrev_b64 v[98:99], 2, v[100:101]
	v_lshl_add_u64 v[96:97], s[26:27], 0, v[98:99]
	global_load_dwordx4 v[228:231], v[96:97], off
	global_load_dwordx4 v[232:235], v[96:97], off offset:64
	global_load_dwordx4 v[236:239], v[96:97], off offset:128
	global_load_dwordx4 v[240:243], v[96:97], off offset:192
	s_and_b64 vcc, exec, s[6:7]
	v_lshl_add_u64 v[98:99], s[90:91], 0, v[98:99]
	s_mov_b64 s[2:3], -1
	s_waitcnt vmcnt(3)
	v_pk_fma_f32 v[94:95], v[94:95], 0.5, v[230:231] op_sel_hi:[1,0,1]
	v_pk_fma_f32 v[92:93], v[92:93], 0.5, v[228:229] op_sel_hi:[1,0,1]
	global_store_dwordx4 v[98:99], v[92:95], off
	s_cbranch_vccnz .LBB0_541
	s_mov_b64 s[2:3], 0

.LBB0_543:
	s_and_b64 vcc, exec, s[6:7]
	s_mov_b64 s[2:3], -1
	s_waitcnt vmcnt(3)
	v_pk_fma_f32 v[90:91], v[90:91], 0.5, v[234:235] op_sel_hi:[1,0,1]
	v_pk_fma_f32 v[88:89], v[88:89], 0.5, v[232:233] op_sel_hi:[1,0,1]
	global_store_dwordx4 v[98:99], v[88:91], off offset:64
	s_cbranch_vccnz .LBB0_545
	s_mov_b64 s[2:3], 0

.LBB0_547:
	s_and_b64 vcc, exec, s[6:7]
	s_mov_b64 s[2:3], -1
	s_waitcnt vmcnt(3)
	v_pk_fma_f32 v[86:87], v[86:87], 0.5, v[238:239] op_sel_hi:[1,0,1]
	v_pk_fma_f32 v[84:85], v[84:85], 0.5, v[236:237] op_sel_hi:[1,0,1]
	global_store_dwordx4 v[98:99], v[84:87], off offset:128
	s_cbranch_vccnz .LBB0_549
	s_mov_b64 s[2:3], 0

.LBB0_551:
	s_and_b64 vcc, exec, s[6:7]
	s_mov_b64 s[2:3], -1
	s_waitcnt vmcnt(3)
	v_pk_fma_f32 v[82:83], v[82:83], 0.5, v[242:243] op_sel_hi:[1,0,1]
	v_pk_fma_f32 v[80:81], v[80:81], 0.5, v[240:241] op_sel_hi:[1,0,1]
	global_store_dwordx4 v[98:99], v[80:83], off offset:192
	s_cbranch_vccnz .LBB0_553
	s_mov_b64 s[2:3], 0

.LBB0_557:
	s_or_b64 exec, exec, s[2:3]
	v_or_b32_e32 v80, 48, v130
	s_waitcnt lgkmcnt(0)
	v_ashrrev_i32_e32 v81, 31, v80
	v_lshlrev_b64 v[80:81], 10, v[80:81]
	v_lshl_add_u64 v[84:85], v[128:129], 0, v[80:81]
	v_lshlrev_b64 v[82:83], 2, v[84:85]
	v_lshl_add_u64 v[80:81], s[26:27], 0, v[82:83]
	global_load_dwordx4 v[228:231], v[80:81], off
	global_load_dwordx4 v[232:235], v[80:81], off offset:64
	global_load_dwordx4 v[236:239], v[80:81], off offset:128
	global_load_dwordx4 v[240:243], v[80:81], off offset:192
	s_and_b64 vcc, exec, s[6:7]
	v_lshl_add_u64 v[82:83], s[90:91], 0, v[82:83]
	s_mov_b64 s[2:3], -1
	s_waitcnt vmcnt(3)
	v_pk_fma_f32 v[78:79], v[78:79], 0.5, v[230:231] op_sel_hi:[1,0,1]
	v_pk_fma_f32 v[76:77], v[76:77], 0.5, v[228:229] op_sel_hi:[1,0,1]
	global_store_dwordx4 v[82:83], v[76:79], off
	s_cbranch_vccnz .LBB0_559
	s_mov_b64 s[2:3], 0

.LBB0_561:
	s_and_b64 vcc, exec, s[6:7]
	s_mov_b64 s[2:3], -1
	s_waitcnt vmcnt(3)
	v_pk_fma_f32 v[74:75], v[74:75], 0.5, v[234:235] op_sel_hi:[1,0,1]
	v_pk_fma_f32 v[72:73], v[72:73], 0.5, v[232:233] op_sel_hi:[1,0,1]
	global_store_dwordx4 v[82:83], v[72:75], off offset:64
	s_cbranch_vccnz .LBB0_563
	s_mov_b64 s[2:3], 0

.LBB0_565:
	s_and_b64 vcc, exec, s[6:7]
	s_mov_b64 s[2:3], -1
	s_waitcnt vmcnt(3)
	v_pk_fma_f32 v[70:71], v[70:71], 0.5, v[238:239] op_sel_hi:[1,0,1]
	v_pk_fma_f32 v[68:69], v[68:69], 0.5, v[236:237] op_sel_hi:[1,0,1]
	global_store_dwordx4 v[82:83], v[68:71], off offset:128
	s_cbranch_vccnz .LBB0_567
	s_mov_b64 s[2:3], 0

.LBB0_569:
	s_and_b64 vcc, exec, s[6:7]
	s_mov_b64 s[2:3], -1
	s_waitcnt vmcnt(3)
	v_pk_fma_f32 v[66:67], v[66:67], 0.5, v[242:243] op_sel_hi:[1,0,1]
	v_pk_fma_f32 v[64:65], v[64:65], 0.5, v[240:241] op_sel_hi:[1,0,1]
	global_store_dwordx4 v[82:83], v[64:67], off offset:192
	s_cbranch_vccnz .LBB0_571
	s_mov_b64 s[2:3], 0

.LBB0_575:
	s_or_b64 exec, exec, s[2:3]
	v_or_b32_e32 v64, 64, v130
	s_waitcnt lgkmcnt(0)
	v_ashrrev_i32_e32 v65, 31, v64
	v_lshlrev_b64 v[64:65], 10, v[64:65]
	v_lshl_add_u64 v[68:69], v[128:129], 0, v[64:65]
	v_lshlrev_b64 v[66:67], 2, v[68:69]
	v_lshl_add_u64 v[64:65], s[26:27], 0, v[66:67]
	global_load_dwordx4 v[228:231], v[64:65], off
	global_load_dwordx4 v[232:235], v[64:65], off offset:64
	global_load_dwordx4 v[236:239], v[64:65], off offset:128
	global_load_dwordx4 v[240:243], v[64:65], off offset:192
	s_and_b64 vcc, exec, s[6:7]
	v_lshl_add_u64 v[66:67], s[90:91], 0, v[66:67]
	s_mov_b64 s[2:3], -1
	s_waitcnt vmcnt(3)
	v_pk_fma_f32 v[62:63], v[62:63], 0.5, v[230:231] op_sel_hi:[1,0,1]
	v_pk_fma_f32 v[60:61], v[60:61], 0.5, v[228:229] op_sel_hi:[1,0,1]
	global_store_dwordx4 v[66:67], v[60:63], off
	s_cbranch_vccnz .LBB0_577
	s_mov_b64 s[2:3], 0

.LBB0_579:
	s_and_b64 vcc, exec, s[6:7]
	s_mov_b64 s[2:3], -1
	s_waitcnt vmcnt(3)
	v_pk_fma_f32 v[58:59], v[58:59], 0.5, v[234:235] op_sel_hi:[1,0,1]
	v_pk_fma_f32 v[56:57], v[56:57], 0.5, v[232:233] op_sel_hi:[1,0,1]
	global_store_dwordx4 v[66:67], v[56:59], off offset:64
	s_cbranch_vccnz .LBB0_581
	s_mov_b64 s[2:3], 0

.LBB0_583:
	s_and_b64 vcc, exec, s[6:7]
	s_mov_b64 s[2:3], -1
	s_waitcnt vmcnt(3)
	v_pk_fma_f32 v[54:55], v[54:55], 0.5, v[238:239] op_sel_hi:[1,0,1]
	v_pk_fma_f32 v[52:53], v[52:53], 0.5, v[236:237] op_sel_hi:[1,0,1]
	global_store_dwordx4 v[66:67], v[52:55], off offset:128
	s_cbranch_vccnz .LBB0_585
	s_mov_b64 s[2:3], 0

.LBB0_587:
	s_and_b64 vcc, exec, s[6:7]
	s_mov_b64 s[2:3], -1
	s_waitcnt vmcnt(3)
	v_pk_fma_f32 v[50:51], v[50:51], 0.5, v[242:243] op_sel_hi:[1,0,1]
	v_pk_fma_f32 v[48:49], v[48:49], 0.5, v[240:241] op_sel_hi:[1,0,1]
	global_store_dwordx4 v[66:67], v[48:51], off offset:192
	s_cbranch_vccnz .LBB0_589
	s_mov_b64 s[2:3], 0

.LBB0_593:
	s_or_b64 exec, exec, s[2:3]
	v_or_b32_e32 v48, 0x50, v130
	s_waitcnt lgkmcnt(0)
	v_ashrrev_i32_e32 v49, 31, v48
	v_lshlrev_b64 v[48:49], 10, v[48:49]
	v_lshl_add_u64 v[52:53], v[128:129], 0, v[48:49]
	v_lshlrev_b64 v[50:51], 2, v[52:53]
	v_lshl_add_u64 v[48:49], s[26:27], 0, v[50:51]
	global_load_dwordx4 v[228:231], v[48:49], off
	global_load_dwordx4 v[232:235], v[48:49], off offset:64
	global_load_dwordx4 v[236:239], v[48:49], off offset:128
	global_load_dwordx4 v[240:243], v[48:49], off offset:192
	s_and_b64 vcc, exec, s[6:7]
	v_lshl_add_u64 v[50:51], s[90:91], 0, v[50:51]
	s_mov_b64 s[2:3], -1
	s_waitcnt vmcnt(3)
	v_pk_fma_f32 v[46:47], v[46:47], 0.5, v[230:231] op_sel_hi:[1,0,1]
	v_pk_fma_f32 v[44:45], v[44:45], 0.5, v[228:229] op_sel_hi:[1,0,1]
	global_store_dwordx4 v[50:51], v[44:47], off
	s_cbranch_vccnz .LBB0_595
	s_mov_b64 s[2:3], 0

.LBB0_597:
	s_and_b64 vcc, exec, s[6:7]
	s_mov_b64 s[2:3], -1
	s_waitcnt vmcnt(3)
	v_pk_fma_f32 v[42:43], v[42:43], 0.5, v[234:235] op_sel_hi:[1,0,1]
	v_pk_fma_f32 v[40:41], v[40:41], 0.5, v[232:233] op_sel_hi:[1,0,1]
	global_store_dwordx4 v[50:51], v[40:43], off offset:64
	s_cbranch_vccnz .LBB0_599
	s_mov_b64 s[2:3], 0

.LBB0_601:
	s_and_b64 vcc, exec, s[6:7]
	s_mov_b64 s[2:3], -1
	s_waitcnt vmcnt(3)
	v_pk_fma_f32 v[38:39], v[38:39], 0.5, v[238:239] op_sel_hi:[1,0,1]
	v_pk_fma_f32 v[36:37], v[36:37], 0.5, v[236:237] op_sel_hi:[1,0,1]
	global_store_dwordx4 v[50:51], v[36:39], off offset:128
	s_cbranch_vccnz .LBB0_603
	s_mov_b64 s[2:3], 0

.LBB0_605:
	s_and_b64 vcc, exec, s[6:7]
	s_mov_b64 s[2:3], -1
	s_waitcnt vmcnt(3)
	v_pk_fma_f32 v[34:35], v[34:35], 0.5, v[242:243] op_sel_hi:[1,0,1]
	v_pk_fma_f32 v[32:33], v[32:33], 0.5, v[240:241] op_sel_hi:[1,0,1]
	global_store_dwordx4 v[50:51], v[32:35], off offset:192
	s_cbranch_vccnz .LBB0_607
	s_mov_b64 s[2:3], 0

.LBB0_611:
	s_or_b64 exec, exec, s[2:3]
	v_or_b32_e32 v32, 0x60, v130
	s_waitcnt lgkmcnt(0)
	v_ashrrev_i32_e32 v33, 31, v32
	v_lshlrev_b64 v[32:33], 10, v[32:33]
	v_lshl_add_u64 v[36:37], v[128:129], 0, v[32:33]
	v_lshlrev_b64 v[34:35], 2, v[36:37]
	v_lshl_add_u64 v[32:33], s[26:27], 0, v[34:35]
	global_load_dwordx4 v[228:231], v[32:33], off
	global_load_dwordx4 v[232:235], v[32:33], off offset:64
	global_load_dwordx4 v[236:239], v[32:33], off offset:128
	global_load_dwordx4 v[240:243], v[32:33], off offset:192
	s_and_b64 vcc, exec, s[6:7]
	v_lshl_add_u64 v[34:35], s[90:91], 0, v[34:35]
	s_mov_b64 s[2:3], -1
	s_waitcnt vmcnt(3)
	v_pk_fma_f32 v[30:31], v[30:31], 0.5, v[230:231] op_sel_hi:[1,0,1]
	v_pk_fma_f32 v[28:29], v[28:29], 0.5, v[228:229] op_sel_hi:[1,0,1]
	global_store_dwordx4 v[34:35], v[28:31], off
	s_cbranch_vccnz .LBB0_613
	s_mov_b64 s[2:3], 0

.LBB0_615:
	s_and_b64 vcc, exec, s[6:7]
	s_mov_b64 s[2:3], -1
	s_waitcnt vmcnt(3)
	v_pk_fma_f32 v[26:27], v[26:27], 0.5, v[234:235] op_sel_hi:[1,0,1]
	v_pk_fma_f32 v[24:25], v[24:25], 0.5, v[232:233] op_sel_hi:[1,0,1]
	global_store_dwordx4 v[34:35], v[24:27], off offset:64
	s_cbranch_vccnz .LBB0_617
	s_mov_b64 s[2:3], 0

.LBB0_619:
	s_and_b64 vcc, exec, s[6:7]
	s_mov_b64 s[2:3], -1
	s_waitcnt vmcnt(3)
	v_pk_fma_f32 v[22:23], v[22:23], 0.5, v[238:239] op_sel_hi:[1,0,1]
	v_pk_fma_f32 v[20:21], v[20:21], 0.5, v[236:237] op_sel_hi:[1,0,1]
	global_store_dwordx4 v[34:35], v[20:23], off offset:128
	s_cbranch_vccnz .LBB0_621
	s_mov_b64 s[2:3], 0

.LBB0_623:
	s_and_b64 vcc, exec, s[6:7]
	s_mov_b64 s[2:3], -1
	s_waitcnt vmcnt(3)
	v_pk_fma_f32 v[18:19], v[18:19], 0.5, v[242:243] op_sel_hi:[1,0,1]
	v_pk_fma_f32 v[16:17], v[16:17], 0.5, v[240:241] op_sel_hi:[1,0,1]
	global_store_dwordx4 v[34:35], v[16:19], off offset:192
	s_cbranch_vccnz .LBB0_625
	s_mov_b64 s[2:3], 0

.LBB0_629:
	s_or_b64 exec, exec, s[2:3]
	v_or_b32_e32 v16, 0x70, v130
	s_waitcnt lgkmcnt(0)
	v_ashrrev_i32_e32 v17, 31, v16
	v_lshlrev_b64 v[16:17], 10, v[16:17]
	v_lshl_add_u64 v[20:21], v[128:129], 0, v[16:17]
	v_lshlrev_b64 v[18:19], 2, v[20:21]
	v_lshl_add_u64 v[16:17], s[26:27], 0, v[18:19]
	global_load_dwordx4 v[228:231], v[16:17], off
	global_load_dwordx4 v[232:235], v[16:17], off offset:64
	global_load_dwordx4 v[236:239], v[16:17], off offset:128
	global_load_dwordx4 v[240:243], v[16:17], off offset:192
	s_and_b64 vcc, exec, s[6:7]
	v_lshl_add_u64 v[18:19], s[90:91], 0, v[18:19]
	s_mov_b64 s[2:3], -1
	s_waitcnt vmcnt(3)
	v_pk_fma_f32 v[14:15], v[14:15], 0.5, v[230:231] op_sel_hi:[1,0,1]
	v_pk_fma_f32 v[12:13], v[12:13], 0.5, v[228:229] op_sel_hi:[1,0,1]
	global_store_dwordx4 v[18:19], v[12:15], off
	s_cbranch_vccnz .LBB0_631
	s_mov_b64 s[2:3], 0

.LBB0_633:
	s_and_b64 vcc, exec, s[6:7]
	s_mov_b64 s[2:3], -1
	s_waitcnt vmcnt(3)
	v_pk_fma_f32 v[10:11], v[10:11], 0.5, v[234:235] op_sel_hi:[1,0,1]
	v_pk_fma_f32 v[8:9], v[8:9], 0.5, v[232:233] op_sel_hi:[1,0,1]
	global_store_dwordx4 v[18:19], v[8:11], off offset:64
	s_cbranch_vccnz .LBB0_635
	s_mov_b64 s[2:3], 0

.LBB0_637:
	s_and_b64 vcc, exec, s[6:7]
	s_mov_b64 s[2:3], -1
	s_waitcnt vmcnt(3)
	v_pk_fma_f32 v[6:7], v[6:7], 0.5, v[238:239] op_sel_hi:[1,0,1]
	v_pk_fma_f32 v[4:5], v[4:5], 0.5, v[236:237] op_sel_hi:[1,0,1]
	global_store_dwordx4 v[18:19], v[4:7], off offset:128
	s_cbranch_vccnz .LBB0_639
	s_mov_b64 s[2:3], 0

.LBB0_641:
	s_and_b64 vcc, exec, s[6:7]
	s_mov_b64 s[2:3], -1
	s_waitcnt vmcnt(3)
	v_pk_fma_f32 v[2:3], v[2:3], 0.5, v[242:243] op_sel_hi:[1,0,1]
	v_pk_fma_f32 v[0:1], v[0:1], 0.5, v[240:241] op_sel_hi:[1,0,1]
	global_store_dwordx4 v[18:19], v[0:3], off offset:192
	s_cbranch_vccnz .LBB0_643
	s_mov_b64 s[2:3], 0
